# GEMM loops: static s_setprio raise for the wr==0 wave half (no per-block toggling)
# speedup vs baseline: 1.0085x; 1.0021x over previous
.LBB0_171:
	s_or_b64 exec, exec, s[0:1]
	s_add_u32 s0, s30, 0xea00000
	s_addc_u32 s1, s31, 0
	s_add_u32 s3, s30, 0xce00000
	v_writelane_b32 v239, s3, 9
	s_addc_u32 s3, s31, 0
	v_writelane_b32 v239, s3, 10
	v_mov_b32_e32 v9, v176
	v_readlane_b32 s4, v239, 2
	s_ashr_i32 s3, s4, 31
	v_readlane_b32 s5, v239, 3
	v_writelane_b32 v239, s3, 11
	s_ashr_i32 s3, s2, 31
	s_waitcnt lgkmcnt(0)
	s_barrier
	s_cmpk_gt_i32 s2, 0x3ef
	s_nop 0
	v_readfirstlane_b32 s36, v9
	s_cbranch_scc1 .LBB0_183
	v_lshlrev_b32_e32 v0, 4, v9
	v_add_u32_e32 v1, 0x2000, v0
	v_ashrrev_i32_e32 v2, 31, v1
	v_lshrrev_b32_e32 v2, 22, v2
	v_add_u32_e32 v2, v1, v2
	v_ashrrev_i32_e32 v8, 10, v2
	v_mul_i32_i24_e32 v2, 0x400, v8
	v_sub_u32_e32 v1, v1, v2
	v_lshrrev_b32_e32 v2, 4, v1
	v_bitop3_b32 v1, v2, v1, 32 bitop3:0x6c
	v_ashrrev_i32_e32 v2, 31, v1
	v_lshrrev_b32_e32 v2, 26, v2
	v_add_u32_e32 v2, v1, v2
	v_lshlrev_b32_e32 v3, 3, v8
	v_ashrrev_i32_e32 v10, 6, v2
	v_and_b32_e32 v3, -16, v3
	v_add_u32_e32 v3, v10, v3
	v_and_b32_e32 v4, 3, v10
	s_mov_b32 s4, 0xfffe0
	v_lshrrev_b32_e32 v5, 2, v3
	v_lshlrev_b32_e32 v6, 1, v3
	v_and_b32_e32 v2, 0xc0, v2
	v_and_or_b32 v4, v3, s4, v4
	v_and_b32_e32 v5, 4, v5
	v_and_b32_e32 v6, 24, v6
	v_sub_u32_e32 v1, v1, v2
	v_mov_b32_e32 v2, 1
	v_or3_b32 v4, v4, v5, v6
	v_lshlrev_b32_e32 v5, 5, v8
	v_ashrrev_i16_sdwa v1, v2, sext(v1) dst_sel:DWORD dst_unused:UNUSED_PAD src0_sel:DWORD src1_sel:BYTE_0
	v_and_b32_e32 v5, 32, v5
	v_bfe_i32 v11, v1, 0, 16
	v_add_lshl_u32 v1, v5, v11, 1
	v_lshl_add_u32 v130, v4, 12, v1
	v_lshl_add_u32 v132, v3, 12, v1
	v_bfe_i32 v1, v9, 27, 1
	v_lshrrev_b32_e32 v1, 22, v1
	v_add_u32_e32 v1, v0, v1
	v_and_b32_e32 v1, 0xfffffc00, v1
	v_sub_u32_e32 v0, v0, v1
	v_lshrrev_b32_e32 v1, 4, v0
	v_bitop3_b32 v1, v1, v0, 32 bitop3:0x6c
	v_ashrrev_i32_e32 v0, 31, v0
	v_lshrrev_b32_e32 v0, 26, v0
	v_add_u32_e32 v0, v1, v0
	v_ashrrev_i32_e32 v12, 6, v0
	v_ashrrev_i32_e32 v0, 31, v9
	v_lshrrev_b32_e32 v0, 26, v0
	v_add_u32_e32 v0, v9, v0
	v_ashrrev_i32_e32 v13, 6, v0
	v_lshlrev_b32_e32 v0, 3, v13
	v_and_b32_e32 v0, -16, v0
	v_add_u32_e32 v0, v12, v0
	v_and_b32_e32 v3, 3, v12
	v_and_or_b32 v3, v0, s4, v3
	s_lshr_b32 s4, s3, 29
	s_add_i32 s4, s2, s4
	s_ashr_i32 s6, s36, 6
	s_ashr_i32 s7, s4, 3
	s_and_b32 s4, s4, -8
	s_ashr_i32 s5, s36, 8
	s_lshl_b32 s37, s6, 10
	s_sub_i32 s4, s2, s4
	s_cmp_lt_i32 s4, 0
	s_movk_i32 s38, 0x7f
	s_cselect_b32 s12, s38, 0x7e
	s_mul_i32 s4, s4, s12
	s_add_i32 s4, s4, s7
	v_lshrrev_b32_e32 v4, 2, v0
	v_lshlrev_b32_e32 v5, 1, v0
	s_mul_hi_i32 s7, s4, 0x92492493
	v_and_b32_e32 v4, 4, v4
	v_and_b32_e32 v5, 24, v5
	s_add_i32 s7, s7, s4
	v_or3_b32 v3, v3, v4, v5
	v_mul_i32_i24_e32 v5, 64, v12
	s_lshr_b32 s12, s7, 31
	s_ashr_i32 s7, s7, 7
	v_sub_u32_e32 v1, v1, v5
	s_add_i32 s7, s7, s12
	v_lshlrev_b32_e32 v4, 5, v13
	v_ashrrev_i16_sdwa v1, v2, sext(v1) dst_sel:DWORD dst_unused:UNUSED_PAD src0_sel:DWORD src1_sel:BYTE_0
	s_lshl_b32 s14, s7, 3
	v_and_b32_e32 v4, 32, v4
	v_bfe_i32 v14, v1, 0, 16
	s_sub_i32 s12, 36, s14
	s_mulk_i32 s7, 0xe0
	v_add_lshl_u32 v1, v4, v14, 1
	s_min_u32 s15, s12, 8
	s_sub_i32 s7, s4, s7
	v_lshl_add_u32 v134, v3, 12, v1
	s_sext_i32_i16 s4, s7
	v_cvt_f32_ubyte0_e32 v3, s15
	v_cvt_f32_i32_e32 v2, s4
	v_rcp_iflag_f32_e32 v4, v3
	v_lshl_add_u32 v136, v0, 12, v1
	s_ashr_i32 s4, s4, 30
	s_or_b32 s4, s4, 1
	v_mul_f32_e32 v0, v2, v4
	v_trunc_f32_e32 v0, v0
	v_fma_f32 v1, -v0, v3, v2
	v_cvt_i32_f32_e32 v0, v0
	v_cmp_ge_f32_e64 s[12:13], |v1|, v3
	s_and_b64 s[12:13], s[12:13], exec
	s_cselect_b32 s4, s4, 0
	v_readfirstlane_b32 s12, v0
	s_add_i32 s4, s12, s4
	s_mul_i32 s12, s4, s15
	s_sub_i32 s7, s7, s12
	s_sext_i32_i16 s7, s7
	s_add_i32 s20, s14, s7
	s_ashr_i32 s21, s20, 31
	s_bfe_i64 s[14:15], s[4:5], 0x100000
	s_lshl_b64 s[12:13], s[20:21], 20
	s_lshl_b64 s[14:15], s[14:15], 20
	v_readlane_b32 s7, v239, 9
	s_add_u32 s24, s7, s14
	v_readlane_b32 s7, v239, 10
	s_addc_u32 s25, s7, s15
	s_add_i32 s21, s37, 0
	s_add_i32 m0, s21, 0x10000
	v_mov_b32_e32 v135, 0
	global_load_lds_dwordx4 v134, s[24:25]
	s_add_i32 m0, s21, 0x12000
	s_add_u32 s22, s0, s12
	global_load_lds_dwordx4 v130, s[24:25]
	s_addc_u32 s23, s1, s13
	s_mov_b32 m0, s21
	s_add_i32 s39, s21, 0x2000
	global_load_lds_dwordx4 v136, s[22:23]
	s_mov_b32 m0, s39
	s_add_u32 s12, s24, 0x80000
	global_load_lds_dwordx4 v132, s[22:23]
	s_addc_u32 s13, s25, 0
	s_add_i32 m0, s21, 0x14000
	v_mov_b32_e32 v131, v135
	global_load_lds_dwordx4 v134, s[12:13]
	s_add_i32 m0, s21, 0x16000
	v_mov_b32_e32 v137, v135
	global_load_lds_dwordx4 v130, s[12:13]
	s_add_u32 s12, s22, 0x80000
	s_addc_u32 s13, s23, 0
	s_add_i32 s40, s21, 0x4000
	s_mov_b32 m0, s40
	s_add_i32 s41, s21, 0x6000
	global_load_lds_dwordx4 v136, s[12:13]
	s_mov_b32 m0, s41
	v_mov_b32_e32 v133, v135
	global_load_lds_dwordx4 v132, s[12:13]
	s_mov_b32 s97, s43
	s_mov_b32 s42, 0
	v_lshl_add_u64 v[6:7], s[24:25], 0, v[134:135]
	v_lshl_add_u64 v[4:5], s[24:25], 0, v[130:131]
	v_lshl_add_u64 v[2:3], s[22:23], 0, v[136:137]
	s_setprio 1
	s_cmp_lg_u32 s5, 1
	v_lshl_add_u64 v[0:1], s[22:23], 0, v[132:133]
	s_cbranch_scc1 .LBB0_174
	s_setprio 0
	s_barrier

.LBB0_678:
	s_or_b64 exec, exec, s[4:5]
	v_mov_b32_e32 v13, v176
	s_barrier
	s_mov_b32 s5, 0xfffe0
	v_ashrrev_i32_e32 v1, 31, v13
	v_lshrrev_b32_e32 v1, 26, v1
	v_add_u32_e32 v1, v13, v1
	v_ashrrev_i32_e32 v8, 6, v1
	v_bfe_i32 v1, v13, 27, 1
	v_lshlrev_b32_e32 v0, 4, v13
	v_lshrrev_b32_e32 v1, 22, v1
	v_add_u32_e32 v1, v0, v1
	v_and_b32_e32 v1, 0xfffffc00, v1
	v_sub_u32_e32 v1, v0, v1
	v_lshrrev_b32_e32 v2, 4, v1
	v_bitop3_b32 v2, v2, v1, 32 bitop3:0x6c
	v_ashrrev_i32_e32 v1, 31, v1
	v_lshrrev_b32_e32 v1, 26, v1
	v_add_u32_e32 v1, v2, v1
	v_ashrrev_i32_e32 v9, 6, v1
	v_lshlrev_b32_e32 v3, 3, v8
	v_mul_i32_i24_e32 v4, 64, v9
	v_and_b32_e32 v3, -16, v3
	v_sub_u32_e32 v2, v2, v4
	v_mov_b32_e32 v4, 1
	v_add_u32_e32 v1, v9, v3
	v_lshlrev_b32_e32 v3, 5, v8
	v_ashrrev_i16_sdwa v2, v4, sext(v2) dst_sel:DWORD dst_unused:UNUSED_PAD src0_sel:DWORD src1_sel:BYTE_0
	v_and_b32_e32 v3, 32, v3
	v_bfe_i32 v10, v2, 0, 16
	v_and_b32_e32 v6, 3, v9
	v_add_lshl_u32 v3, v3, v10, 1
	v_add_u32_e32 v0, 0x2000, v0
	v_lshlrev_b32_e32 v2, 1, v1
	v_lshrrev_b32_e32 v5, 2, v1
	v_and_or_b32 v6, v1, s5, v6
	v_lshl_add_u32 v128, v1, 12, v3
	v_ashrrev_i32_e32 v1, 31, v0
	v_lshrrev_b32_e32 v1, 22, v1
	v_add_u32_e32 v1, v0, v1
	v_ashrrev_i32_e32 v11, 10, v1
	v_mul_i32_i24_e32 v1, 0x400, v11
	v_sub_u32_e32 v0, v0, v1
	v_and_b32_e32 v2, 24, v2
	v_and_b32_e32 v5, 4, v5
	v_lshrrev_b32_e32 v1, 4, v0
	v_or3_b32 v2, v6, v5, v2
	v_bitop3_b32 v0, v1, v0, 32 bitop3:0x6c
	v_lshl_add_u32 v130, v2, 12, v3
	v_ashrrev_i32_e32 v2, 31, v0
	v_lshrrev_b32_e32 v2, 26, v2
	v_add_u32_e32 v2, v0, v2
	v_lshlrev_b32_e32 v1, 3, v11
	v_ashrrev_i32_e32 v12, 6, v2
	v_and_b32_e32 v2, 0xc0, v2
	s_sub_i32 s4, s68, s8
	v_and_b32_e32 v1, -16, v1
	v_sub_u32_e32 v0, v0, v2
	s_ashr_i32 s4, s4, 3
	v_readfirstlane_b32 s20, v13
	v_add_u32_e32 v1, v12, v1
	v_ashrrev_i16_sdwa v0, v4, sext(v0) dst_sel:DWORD dst_unused:UNUSED_PAD src0_sel:DWORD src1_sel:BYTE_0
	v_and_b32_e32 v4, 3, v12
	s_add_i32 s4, s4, 32
	s_and_b32 s22, s2, 7
	s_ashr_i32 s10, s20, 6
	v_and_or_b32 v4, v1, s5, v4
	s_mov_b32 s5, 0
	s_ashr_i32 s11, s20, 8
	s_lshl_b32 s16, s10, 10
	s_lshl_b64 s[12:13], s[4:5], 20
	s_lshl_b32 s14, s22, 20
	s_add_u32 s15, s30, s14
	s_addc_u32 s17, s31, 0
	s_add_u32 s6, s15, 0x13200000
	s_addc_u32 s7, s17, 0
	s_add_i32 s5, s16, 0
	s_add_i32 m0, s5, 0x10000
	v_lshlrev_b32_e32 v3, 5, v11
	v_bfe_i32 v14, v0, 0, 16
	v_lshlrev_b32_e32 v0, 1, v1
	v_lshrrev_b32_e32 v2, 2, v1
	global_load_lds_dwordx4 v130, s[6:7]
	s_add_i32 m0, s5, 0x12000
	v_and_b32_e32 v3, 32, v3
	v_and_b32_e32 v0, 24, v0
	v_and_b32_e32 v2, 4, v2
	s_add_u32 s21, s30, s12
	v_or3_b32 v0, v4, v2, v0
	v_add_lshl_u32 v2, v3, v14, 1
	s_addc_u32 s24, s31, s13
	v_lshl_add_u32 v134, v0, 12, v2
	s_add_u32 s8, s21, 0x10e00000
	global_load_lds_dwordx4 v134, s[6:7]
	s_addc_u32 s9, s24, 0
	s_mov_b32 m0, s5
	s_add_i32 s23, s5, 0x2000
	v_lshl_add_u32 v132, v1, 12, v2
	global_load_lds_dwordx4 v128, s[8:9]
	s_mov_b32 m0, s23
	s_add_u32 s18, s15, 0x13280000
	global_load_lds_dwordx4 v132, s[8:9]
	s_addc_u32 s19, s17, 0
	s_add_i32 m0, s5, 0x14000
	v_mov_b32_e32 v131, 0
	global_load_lds_dwordx4 v130, s[18:19]
	s_add_i32 m0, s5, 0x16000
	v_mov_b32_e32 v135, v131
	global_load_lds_dwordx4 v134, s[18:19]
	s_add_u32 s18, s21, 0x10e80000
	s_addc_u32 s19, s24, 0
	s_add_i32 s24, s5, 0x4000
	s_mov_b32 m0, s24
	s_add_i32 s25, s5, 0x6000
	global_load_lds_dwordx4 v128, s[18:19]
	s_mov_b32 m0, s25
	v_mov_b32_e32 v129, v131
	global_load_lds_dwordx4 v132, s[18:19]
	v_mov_b32_e32 v133, v131
	v_lshl_add_u64 v[6:7], s[6:7], 0, v[130:131]
	v_lshl_add_u64 v[4:5], s[6:7], 0, v[134:135]
	v_lshl_add_u64 v[2:3], s[8:9], 0, v[128:129]
	s_setprio 1
	s_cmp_lg_u32 s11, 1
	v_lshl_add_u64 v[0:1], s[8:9], 0, v[132:133]
	s_cbranch_scc1 .LBB0_680
	s_setprio 0
	s_barrier

.LBB0_856:
	s_add_u32 s8, s30, 0x17d29000
	s_addc_u32 s9, s31, 0
	s_andn2_b64 vcc, exec, s[4:5]
	s_cbranch_vccnz .LBB0_888
	v_ashrrev_i32_e32 v1, 31, v9
	v_lshrrev_b32_e32 v1, 26, v1
	v_add_u32_e32 v1, v9, v1
	v_ashrrev_i32_e32 v8, 6, v1
	v_bfe_i32 v1, v9, 27, 1
	v_lshlrev_b32_e32 v0, 4, v9
	v_lshrrev_b32_e32 v1, 22, v1
	v_add_u32_e32 v1, v0, v1
	v_and_b32_e32 v1, 0xfffffc00, v1
	v_sub_u32_e32 v1, v0, v1
	v_lshrrev_b32_e32 v2, 4, v1
	v_bitop3_b32 v2, v2, v1, 32 bitop3:0x6c
	v_ashrrev_i32_e32 v1, 31, v1
	v_lshrrev_b32_e32 v1, 26, v1
	v_add_u32_e32 v1, v2, v1
	v_ashrrev_i32_e32 v10, 6, v1
	v_lshlrev_b32_e32 v3, 3, v8
	v_mul_i32_i24_e32 v4, 64, v10
	v_and_b32_e32 v3, -16, v3
	v_sub_u32_e32 v2, v2, v4
	v_mov_b32_e32 v4, 1
	v_add_u32_e32 v1, v10, v3
	v_lshlrev_b32_e32 v3, 5, v8
	v_ashrrev_i16_sdwa v2, v4, sext(v2) dst_sel:DWORD dst_unused:UNUSED_PAD src0_sel:DWORD src1_sel:BYTE_0
	v_and_b32_e32 v3, 32, v3
	v_bfe_i32 v11, v2, 0, 16
	v_and_b32_e32 v6, 3, v10
	s_mov_b32 s5, 0xfffe0
	v_add_lshl_u32 v3, v3, v11, 1
	v_add_u32_e32 v0, 0x2000, v0
	v_lshlrev_b32_e32 v2, 1, v1
	v_lshrrev_b32_e32 v5, 2, v1
	v_and_or_b32 v6, v1, s5, v6
	v_lshl_add_u32 v182, v1, 12, v3
	v_ashrrev_i32_e32 v1, 31, v0
	v_lshrrev_b32_e32 v1, 22, v1
	v_add_u32_e32 v1, v0, v1
	v_ashrrev_i32_e32 v12, 10, v1
	v_mul_i32_i24_e32 v1, 0x400, v12
	v_sub_u32_e32 v0, v0, v1
	v_and_b32_e32 v2, 24, v2
	v_and_b32_e32 v5, 4, v5
	v_lshrrev_b32_e32 v1, 4, v0
	v_or3_b32 v2, v6, v5, v2
	v_bitop3_b32 v0, v1, v0, 32 bitop3:0x6c
	v_lshl_add_u32 v184, v2, 12, v3
	v_ashrrev_i32_e32 v2, 31, v0
	v_lshrrev_b32_e32 v2, 26, v2
	s_add_u32 s35, s30, 0x10e00000
	v_add_u32_e32 v2, v0, v2
	s_addc_u32 s38, s31, 0
	v_lshlrev_b32_e32 v1, 3, v12
	v_ashrrev_i32_e32 v13, 6, v2
	v_and_b32_e32 v2, 0xc0, v2
	s_add_u32 s39, s30, 0x13200000
	v_and_b32_e32 v1, -16, v1
	v_sub_u32_e32 v0, v0, v2
	s_addc_u32 s40, s31, 0
	s_ashr_i32 s4, s33, 6
	v_add_u32_e32 v1, v13, v1
	v_ashrrev_i16_sdwa v0, v4, sext(v0) dst_sel:DWORD dst_unused:UNUSED_PAD src0_sel:DWORD src1_sel:BYTE_0
	v_and_b32_e32 v4, 3, v13
	s_ashr_i32 s13, s12, 31
	s_ashr_i32 s11, s10, 31
	v_and_or_b32 v4, v1, s5, v4
	s_ashr_i32 s5, s33, 8
	s_lshl_b32 s41, s4, 10
	s_lshl_b64 s[6:7], s[12:13], 20
	s_lshl_b64 s[14:15], s[10:11], 20
	s_add_u32 s26, s39, s14
	v_lshlrev_b32_e32 v3, 5, v12
	v_bfe_i32 v14, v0, 0, 16
	v_lshlrev_b32_e32 v0, 1, v1
	v_lshrrev_b32_e32 v2, 2, v1
	s_addc_u32 s27, s40, s15
	s_add_i32 s11, s41, 0
	v_and_b32_e32 v3, 32, v3
	v_and_b32_e32 v0, 24, v0
	v_and_b32_e32 v2, 4, v2
	s_add_i32 m0, s11, 0x10000
	v_or3_b32 v0, v4, v2, v0
	v_add_lshl_u32 v2, v3, v14, 1
	global_load_lds_dwordx4 v184, s[26:27]
	s_add_i32 m0, s11, 0x12000
	v_lshl_add_u32 v188, v0, 12, v2
	s_add_u32 s24, s35, s6
	global_load_lds_dwordx4 v188, s[26:27]
	s_addc_u32 s25, s38, s7
	s_mov_b32 m0, s11
	s_add_i32 s42, s11, 0x2000
	v_lshl_add_u32 v186, v1, 12, v2
	global_load_lds_dwordx4 v182, s[24:25]
	s_mov_b32 m0, s42
	s_add_u32 s6, s26, 0x80000
	global_load_lds_dwordx4 v186, s[24:25]
	s_addc_u32 s7, s27, 0
	s_add_i32 m0, s11, 0x14000
	v_mov_b32_e32 v185, 0
	global_load_lds_dwordx4 v184, s[6:7]
	s_add_i32 m0, s11, 0x16000
	v_mov_b32_e32 v189, v185
	global_load_lds_dwordx4 v188, s[6:7]
	s_add_u32 s6, s24, 0x80000
	s_addc_u32 s7, s25, 0
	s_add_i32 s43, s11, 0x4000
	s_mov_b32 m0, s43
	s_add_i32 s44, s11, 0x6000
	global_load_lds_dwordx4 v182, s[6:7]
	s_mov_b32 m0, s44
	v_mov_b32_e32 v183, v185
	global_load_lds_dwordx4 v186, s[6:7]
	v_mov_b32_e32 v187, v185
	s_movk_i32 s45, 0x2000
	s_mov_b32 s13, 0
	v_lshl_add_u64 v[6:7], s[26:27], 0, v[184:185]
	v_lshl_add_u64 v[4:5], s[26:27], 0, v[188:189]
	v_lshl_add_u64 v[2:3], s[24:25], 0, v[182:183]
	s_setprio 1
	s_cmp_lg_u32 s5, 1
	v_lshl_add_u64 v[0:1], s[24:25], 0, v[186:187]
	s_cbranch_scc1 .LBB0_859
	s_setprio 0
	s_barrier

.Lt5_sel:
	s_ashr_i32 s17, s16, 31
	s_bfe_i64 s[12:13], s[4:5], 0x100000
	s_lshl_b64 s[10:11], s[16:17], 20
	s_lshl_b64 s[12:13], s[12:13], 20
	v_readlane_b32 s14, v239, 7
	v_readlane_b32 s15, v239, 8
	s_add_u32 s20, s14, s12
	s_addc_u32 s21, s15, s13
	s_add_i32 s17, s25, 0
	s_add_i32 m0, s17, 0x10000
	v_mov_b32_e32 v133, 0
	global_load_lds_dwordx4 v132, s[20:21]
	s_add_i32 m0, s17, 0x12000
	s_add_u32 s18, s0, s10
	global_load_lds_dwordx4 v128, s[20:21]
	s_addc_u32 s19, s1, s11
	s_mov_b32 m0, s17
	s_add_i32 s27, s17, 0x2000
	global_load_lds_dwordx4 v134, s[18:19]
	s_mov_b32 m0, s27
	s_add_u32 s10, s20, 0x80000
	global_load_lds_dwordx4 v130, s[18:19]
	s_addc_u32 s11, s21, 0
	s_add_i32 m0, s17, 0x14000
	v_mov_b32_e32 v129, v133
	global_load_lds_dwordx4 v132, s[10:11]
	s_add_i32 m0, s17, 0x16000
	v_mov_b32_e32 v135, v133
	global_load_lds_dwordx4 v128, s[10:11]
	s_add_u32 s10, s18, 0x80000
	s_addc_u32 s11, s19, 0
	s_add_i32 s33, s17, 0x4000
	s_mov_b32 m0, s33
	s_add_i32 s35, s17, 0x6000
	global_load_lds_dwordx4 v134, s[10:11]
	s_mov_b32 m0, s35
	v_mov_b32_e32 v131, v133
	global_load_lds_dwordx4 v130, s[10:11]
	s_lshl_b32 s36, s97, 8
	v_lshl_add_u64 v[6:7], s[20:21], 0, v[132:133]
	v_lshl_add_u64 v[4:5], s[20:21], 0, v[128:129]
	v_lshl_add_u64 v[2:3], s[18:19], 0, v[134:135]
	s_setprio 1
	s_cmp_lg_u32 s6, 1
	v_lshl_add_u64 v[0:1], s[18:19], 0, v[130:131]
	s_cbranch_scc1 .LBB0_939
	s_setprio 0
	s_barrier

.LBB0_1069:
	s_or_b64 exec, exec, s[0:1]
	v_mov_b32_e32 v16, v176
	s_waitcnt lgkmcnt(0)
	s_barrier
	s_cmpk_lt_i32 s2, 0x240
	v_readfirstlane_b32 s18, v16
	s_cbranch_scc0 .LBB0_1089
	v_lshlrev_b32_e32 v0, 4, v16
	v_add_u32_e32 v1, 0x2000, v0
	v_ashrrev_i32_e32 v2, 31, v1
	v_lshrrev_b32_e32 v2, 22, v2
	v_add_u32_e32 v2, v1, v2
	v_ashrrev_i32_e32 v8, 10, v2
	v_mul_i32_i24_e32 v2, 0x400, v8
	v_sub_u32_e32 v1, v1, v2
	v_lshrrev_b32_e32 v2, 4, v1
	v_bitop3_b32 v1, v2, v1, 32 bitop3:0x6c
	v_ashrrev_i32_e32 v2, 31, v1
	v_lshrrev_b32_e32 v2, 26, v2
	v_add_u32_e32 v2, v1, v2
	v_lshlrev_b32_e32 v3, 3, v8
	v_ashrrev_i32_e32 v9, 6, v2
	v_and_b32_e32 v3, -16, v3
	v_add_u32_e32 v3, v9, v3
	v_and_b32_e32 v4, 3, v9
	s_mov_b32 s5, 0x7fffe0
	v_lshrrev_b32_e32 v5, 2, v3
	v_lshlrev_b32_e32 v6, 1, v3
	v_and_b32_e32 v2, 0xc0, v2
	v_and_or_b32 v4, v3, s5, v4
	v_and_b32_e32 v5, 4, v5
	v_and_b32_e32 v6, 24, v6
	v_sub_u32_e32 v1, v1, v2
	v_mov_b32_e32 v2, 1
	v_or3_b32 v4, v4, v5, v6
	v_lshlrev_b32_e32 v5, 5, v8
	v_ashrrev_i16_sdwa v1, v2, sext(v1) dst_sel:DWORD dst_unused:UNUSED_PAD src0_sel:DWORD src1_sel:BYTE_0
	s_movk_i32 s4, 0x1600
	v_and_b32_e32 v10, 32, v5
	v_bfe_i32 v11, v1, 0, 16
	v_mul_u32_u24_e32 v4, 0x1600, v4
	v_add_u32_e32 v1, v10, v11
	v_mul_lo_u32 v3, v3, s4
	v_add_lshl_u32 v128, v4, v1, 1
	v_add_lshl_u32 v130, v1, v3, 1
	v_bfe_i32 v1, v16, 27, 1
	v_lshrrev_b32_e32 v1, 22, v1
	v_add_u32_e32 v1, v0, v1
	v_and_b32_e32 v1, 0xfffffc00, v1
	v_sub_u32_e32 v0, v0, v1
	v_lshrrev_b32_e32 v1, 4, v0
	v_bitop3_b32 v1, v1, v0, 32 bitop3:0x6c
	v_ashrrev_i32_e32 v0, 31, v0
	v_lshrrev_b32_e32 v0, 26, v0
	v_add_u32_e32 v0, v1, v0
	v_ashrrev_i32_e32 v12, 6, v0
	v_ashrrev_i32_e32 v0, 31, v16
	v_lshrrev_b32_e32 v0, 26, v0
	v_add_u32_e32 v0, v16, v0
	v_ashrrev_i32_e32 v13, 6, v0
	v_lshlrev_b32_e32 v0, 3, v13
	v_and_b32_e32 v0, -16, v0
	v_add_u32_e32 v0, v12, v0
	v_and_b32_e32 v3, 3, v12
	v_and_or_b32 v3, v0, s5, v3
	s_ashr_i32 s1, s18, 6
	s_ashr_i32 s0, s18, 8
	s_lshl_b32 s19, s1, 10
	v_lshrrev_b32_e32 v4, 2, v0
	v_lshlrev_b32_e32 v5, 1, v0
	v_and_b32_e32 v4, 4, v4
	v_and_b32_e32 v5, 24, v5
	s_and_b32 s5, s2, 7
	s_mul_i32 s100, s5, 50
	s_add_i32 s101, s100, 48
	s_add_i32 s100, s100, -2
	s_max_i32 s100, s100, 0
	s_min_i32 s101, s101, 0x18c

	s_mul_i32 s6, s100, 0x5d2
	s_lshr_b32 s6, s6, 16
	s_mul_i32 s7, s6, 44
	s_sub_i32 s8, s100, s7
	s_add_i32 s7, s7, 44
	s_min_i32 s7, s7, s101
	s_sub_i32 s7, s7, s100
	s_cmp_eq_u32 s7, 44
	s_cselect_b32 s7, 42, s7
	s_add_i32 s100, s100, s7

	s_lshl_b32 s98, s7, 1
	s_add_i32 s98, s98, -4
	s_cmp_lg_u32 s8, 0
	s_cselect_b32 s43, 1, 0
	s_lshr_b32 s9, s2, 6
	s_lshl_b32 s6, s6, 2
	s_add_i32 s42, s6, s9
	s_bfe_u32 s44, s2, 0x30003
	s_lshl_b32 s7, s8, 8
	s_mov_b32 s8, 0
	v_or3_b32 v3, v3, v4, v5
	v_lshlrev_b32_e32 v4, 5, v13
	s_mul_i32 s9, s44, 0x2c0000
	v_and_b32_e32 v14, 32, v4
	v_mul_i32_i24_e32 v4, 64, v12
	s_ashr_i32 s10, s9, 31
	v_readlane_b32 s12, v238, 23
	v_sub_u32_e32 v1, v1, v4
	v_readlane_b32 s13, v238, 24
	s_add_u32 s9, s12, s9
	v_ashrrev_i16_sdwa v1, v2, sext(v1) dst_sel:DWORD dst_unused:UNUSED_PAD src0_sel:DWORD src1_sel:BYTE_0
	s_addc_u32 s10, s13, s10
	v_bfe_i32 v15, v1, 0, 16
	s_add_u32 s12, s9, s7
	v_mul_u32_u24_e32 v3, 0x1600, v3
	v_add_u32_e32 v1, v14, v15
	s_addc_u32 s13, s10, s8
	s_add_i32 s21, s19, 0
	v_add_lshl_u32 v132, v3, v1, 1
	s_add_i32 m0, s21, 0x10000
	s_mul_i32 s6, s42, 0x2c0000
	global_load_lds_dwordx4 v132, s[12:13]
	s_add_i32 m0, s21, 0x12000
	v_readlane_b32 s9, v239, 9
	s_mul_hi_i32 s5, s42, 0x2c0000
	s_add_u32 s6, s9, s6
	v_readlane_b32 s9, v239, 10
	s_addc_u32 s5, s9, s5
	v_mul_lo_u32 v0, v0, s4
	s_add_u32 s10, s6, s7
	v_add_lshl_u32 v134, v1, v0, 1
	global_load_lds_dwordx4 v128, s[12:13]
	s_addc_u32 s11, s5, s8
	s_mov_b32 m0, s21
	s_add_i32 s22, s21, 0x2000
	global_load_lds_dwordx4 v134, s[10:11]
	s_mov_b32 m0, s22
	s_add_u32 s6, s12, 0x160000
	global_load_lds_dwordx4 v130, s[10:11]
	s_addc_u32 s7, s13, 0
	s_add_i32 m0, s21, 0x14000
	v_mov_b32_e32 v133, 0
	global_load_lds_dwordx4 v132, s[6:7]
	s_add_i32 m0, s21, 0x16000
	v_mov_b32_e32 v129, v133
	global_load_lds_dwordx4 v128, s[6:7]
	s_add_u32 s6, s10, 0x160000
	s_addc_u32 s7, s11, 0
	s_add_i32 s23, s21, 0x4000
	s_mov_b32 m0, s23
	s_add_i32 s24, s21, 0x6000
	global_load_lds_dwordx4 v134, s[6:7]
	s_mov_b32 m0, s24
	v_mov_b32_e32 v135, v133
	global_load_lds_dwordx4 v130, s[6:7]
	v_mov_b32_e32 v131, v133
	s_movk_i32 s25, 0x2000
	s_mov_b32 s26, 0
	v_lshl_add_u64 v[6:7], s[12:13], 0, v[132:133]
	v_lshl_add_u64 v[4:5], s[12:13], 0, v[128:129]
	v_lshl_add_u64 v[2:3], s[10:11], 0, v[134:135]
	v_lshl_add_u64 v[0:1], s[10:11], 0, v[130:131]
	s_setprio 1
	s_cmp_lg_u32 s0, 1
	s_mov_b32 s5, 0x16000
	s_cbranch_scc1 .LBB0_1072
	s_setprio 0
	s_barrier
